# ssd_pass2: chunk-decay (CD) pairs of a round loaded together with the state tiles instead of 7 serialized load+wait round trips
# baseline (speedup 1.0000x reference)
.LBB0_470:
	s_movk_i32 s4, 0xa000
	v_add_co_u32_e32 v4, vcc, s4, v138
	s_movk_i32 s4, 0xc000
	s_nop 0
	v_addc_co_u32_e32 v5, vcc, -1, v139, vcc
	v_add_co_u32_e32 v6, vcc, s4, v138
	s_movk_i32 s4, 0xe000
	s_nop 0
	v_addc_co_u32_e32 v7, vcc, -1, v139, vcc
	global_load_dwordx4 v[128:131], v[4:5], off
	global_load_dwordx4 v[124:127], v[6:7], off
	v_add_co_u32_e32 v4, vcc, s4, v138
	s_add_i32 s4, s1, -9
	s_max_i32 s34, s4, 0
	v_addc_co_u32_e32 v5, vcc, -1, v139, vcc
	s_lshl_b64 s[4:5], s[34:35], 16
	global_load_dwordx4 v[120:123], v[4:5], off
	global_load_dwordx4 v[112:115], v[138:139], off
	v_lshl_add_u64 v[4:5], v[136:137], 0, s[4:5]
	v_add_co_u32_e32 v6, vcc, s2, v4
	s_add_i32 s4, s1, -10
	s_nop 0
	v_addc_co_u32_e32 v7, vcc, 0, v5, vcc
	global_load_dwordx4 v[116:119], v[4:5], off
	global_load_dwordx4 v[108:111], v[6:7], off
	v_add_co_u32_e32 v6, vcc, s36, v4
	s_max_i32 s34, s4, 0
	s_nop 0
	v_addc_co_u32_e32 v7, vcc, 0, v5, vcc
	v_add_co_u32_e32 v4, vcc, s37, v4
	s_lshl_b64 s[4:5], s[34:35], 16
	s_nop 0
	v_addc_co_u32_e32 v5, vcc, 0, v5, vcc
	global_load_dwordx4 v[104:107], v[6:7], off
	global_load_dwordx4 v[100:103], v[4:5], off
	v_lshl_add_u64 v[4:5], v[136:137], 0, s[4:5]
	v_add_co_u32_e32 v6, vcc, s2, v4
	s_add_i32 s4, s1, -11
	s_nop 0
	v_addc_co_u32_e32 v7, vcc, 0, v5, vcc
	global_load_dwordx4 v[96:99], v[4:5], off
	global_load_dwordx4 v[92:95], v[6:7], off
	v_add_co_u32_e32 v6, vcc, s36, v4
	s_max_i32 s34, s4, 0
	s_nop 0
	v_addc_co_u32_e32 v7, vcc, 0, v5, vcc
	v_add_co_u32_e32 v4, vcc, s37, v4
	s_lshl_b64 s[4:5], s[34:35], 16
	s_nop 0
	v_addc_co_u32_e32 v5, vcc, 0, v5, vcc
	global_load_dwordx4 v[88:91], v[6:7], off
	global_load_dwordx4 v[84:87], v[4:5], off
	v_lshl_add_u64 v[4:5], v[136:137], 0, s[4:5]
	v_add_co_u32_e32 v6, vcc, s2, v4
	s_add_i32 s4, s1, -12
	s_nop 0
	v_addc_co_u32_e32 v7, vcc, 0, v5, vcc
	global_load_dwordx4 v[80:83], v[4:5], off
	global_load_dwordx4 v[76:79], v[6:7], off
	v_add_co_u32_e32 v6, vcc, s36, v4
	s_max_i32 s34, s4, 0
	s_nop 0
	v_addc_co_u32_e32 v7, vcc, 0, v5, vcc
	v_add_co_u32_e32 v4, vcc, s37, v4
	s_lshl_b64 s[4:5], s[34:35], 16
	s_nop 0
	v_addc_co_u32_e32 v5, vcc, 0, v5, vcc
	global_load_dwordx4 v[72:75], v[6:7], off
	global_load_dwordx4 v[68:71], v[4:5], off
	v_lshl_add_u64 v[4:5], v[136:137], 0, s[4:5]
	v_add_co_u32_e32 v6, vcc, s2, v4
	s_add_i32 s4, s1, -13
	s_nop 0
	v_addc_co_u32_e32 v7, vcc, 0, v5, vcc
	global_load_dwordx4 v[64:67], v[4:5], off
	global_load_dwordx4 v[60:63], v[6:7], off
	v_add_co_u32_e32 v6, vcc, s36, v4
	s_max_i32 s34, s4, 0
	s_nop 0
	v_addc_co_u32_e32 v7, vcc, 0, v5, vcc
	v_add_co_u32_e32 v4, vcc, s37, v4
	s_lshl_b64 s[4:5], s[34:35], 16
	s_nop 0
	v_addc_co_u32_e32 v5, vcc, 0, v5, vcc
	global_load_dwordx4 v[56:59], v[6:7], off
	global_load_dwordx4 v[52:55], v[4:5], off
	v_lshl_add_u64 v[4:5], v[136:137], 0, s[4:5]
	v_add_co_u32_e32 v6, vcc, s2, v4
	s_add_i32 s4, s1, -14
	s_nop 0
	v_addc_co_u32_e32 v7, vcc, 0, v5, vcc
	global_load_dwordx4 v[48:51], v[4:5], off
	global_load_dwordx4 v[44:47], v[6:7], off
	v_add_co_u32_e32 v6, vcc, s36, v4
	s_max_i32 s34, s4, 0
	s_nop 0
	v_addc_co_u32_e32 v7, vcc, 0, v5, vcc
	v_add_co_u32_e32 v4, vcc, s37, v4
	s_lshl_b64 s[4:5], s[34:35], 16
	s_nop 0
	v_addc_co_u32_e32 v5, vcc, 0, v5, vcc
	global_load_dwordx4 v[40:43], v[6:7], off
	global_load_dwordx4 v[36:39], v[4:5], off
	v_lshl_add_u64 v[4:5], v[136:137], 0, s[4:5]
	v_add_co_u32_e32 v6, vcc, s2, v4
	s_add_i32 s4, s1, -15
	s_nop 0
	v_addc_co_u32_e32 v7, vcc, 0, v5, vcc
	global_load_dwordx4 v[32:35], v[4:5], off
	global_load_dwordx4 v[28:31], v[6:7], off
	v_add_co_u32_e32 v6, vcc, s36, v4
	s_max_i32 s34, s4, 0
	s_nop 0
	v_addc_co_u32_e32 v7, vcc, 0, v5, vcc
	v_add_co_u32_e32 v4, vcc, s37, v4
	s_lshl_b64 s[4:5], s[34:35], 16
	s_nop 0
	v_addc_co_u32_e32 v5, vcc, 0, v5, vcc
	global_load_dwordx4 v[24:27], v[6:7], off
	global_load_dwordx4 v[20:23], v[4:5], off
	v_lshl_add_u64 v[4:5], v[136:137], 0, s[4:5]
	s_add_i32 s4, s18, 28
	v_add_co_u32_e32 v6, vcc, s2, v4
	s_ashr_i32 s5, s4, 31
	s_nop 0
	v_addc_co_u32_e32 v7, vcc, 0, v5, vcc
	s_lshl_b64 s[4:5], s[4:5], 2
	global_load_dwordx4 v[16:19], v[4:5], off
	global_load_dwordx4 v[8:11], v[6:7], off
	s_add_u32 s4, s14, s4
	v_add_co_u32_e32 v6, vcc, s36, v4
	s_addc_u32 s5, s15, s5
	s_nop 0
	v_addc_co_u32_e32 v7, vcc, 0, v5, vcc
	global_load_dwordx2 v[156:157], v3, s[4:5]
	global_load_dwordx2 v[240:241], v3, s[4:5] offset:-16
	global_load_dwordx2 v[242:243], v3, s[4:5] offset:-32
	global_load_dwordx2 v[244:245], v3, s[4:5] offset:-48
	global_load_dwordx2 v[246:247], v3, s[4:5] offset:-64
	global_load_dwordx2 v[248:249], v3, s[4:5] offset:-80
	global_load_dwordx2 v[250:251], v3, s[4:5] offset:-96
	global_load_dword v135, v3, s[4:5] offset:-112
	global_load_dword v199, v3, s[4:5] offset:-108
	v_add_co_u32_e32 v4, vcc, s37, v4
	s_cmp_eq_u32 s1, 8
	s_nop 0
	v_addc_co_u32_e32 v5, vcc, 0, v5, vcc
	global_load_dwordx4 v[12:15], v[6:7], off
	s_nop 0
	global_load_dwordx4 v[4:7], v[4:5], off
	s_cselect_b64 s[46:47], -1, 0
	s_and_b64 vcc, exec, s[46:47]
	s_waitcnt vmcnt(2)
	v_pk_mul_f32 v[196:197], v[182:183], v[156:157]
	s_nop 0
	v_mov_b32_e32 v195, v197
	v_mov_b32_e32 v194, v196
	v_mov_b64_e32 v[156:157], v[196:197]
	s_cbranch_vccnz .LBB0_472
	v_pk_mul_f32 v[194:195], v[196:197], v[240:241]
	s_nop 0
	v_mov_b64_e32 v[156:157], v[194:195]
.LBB0_472:
	s_add_i32 s1, s1, -8
	s_cmp_gt_u32 s1, 1
	s_cselect_b64 s[44:45], -1, 0
	s_cmp_lt_u32 s1, 2
	v_mov_b32_e32 v193, v195
	v_mov_b32_e32 v192, v194
	s_cbranch_scc1 .LBB0_474
	v_pk_mul_f32 v[192:193], v[156:157], v[242:243]
	s_nop 0
	v_mov_b64_e32 v[156:157], v[192:193]
.LBB0_474:
	s_cmp_gt_u32 s1, 2
	s_cselect_b64 s[42:43], -1, 0
	s_cmp_lt_u32 s1, 3
	v_mov_b32_e32 v191, v193
	v_mov_b32_e32 v190, v192
	s_cbranch_scc1 .LBB0_476
	v_pk_mul_f32 v[190:191], v[156:157], v[244:245]
	s_nop 0
	v_mov_b64_e32 v[156:157], v[190:191]
.LBB0_476:
	s_cmp_gt_u32 s1, 3
	s_cselect_b64 s[8:9], -1, 0
	s_cmp_lt_u32 s1, 4
	v_mov_b32_e32 v189, v191
	v_mov_b32_e32 v188, v190
	s_cbranch_scc1 .LBB0_478
	v_pk_mul_f32 v[188:189], v[156:157], v[246:247]
	s_nop 0
	v_mov_b64_e32 v[156:157], v[188:189]
.LBB0_478:
	s_cmp_gt_u32 s1, 4
	s_cselect_b64 s[6:7], -1, 0
	s_cmp_lt_u32 s1, 5
	v_mov_b32_e32 v187, v189
	v_mov_b32_e32 v186, v188
	s_cbranch_scc1 .LBB0_480
	v_pk_mul_f32 v[186:187], v[156:157], v[248:249]
	s_nop 0
	v_mov_b64_e32 v[156:157], v[186:187]
.LBB0_480:
	s_cmp_gt_u32 s1, 5
	s_cselect_b64 s[4:5], -1, 0
	s_cmp_lt_u32 s1, 6
	v_mov_b32_e32 v185, v187
	v_mov_b32_e32 v184, v186
	s_cbranch_scc1 .LBB0_482
	v_pk_mul_f32 v[184:185], v[156:157], v[250:251]
	s_nop 0
	v_mov_b64_e32 v[156:157], v[184:185]
.LBB0_482:
	s_cmp_gt_u32 s1, 6
	s_cselect_b64 vcc, -1, 0
	s_cmp_lt_u32 s1, 7
	s_cbranch_scc1 .LBB0_469
	v_mov_b32_e32 v200, v135
	v_mov_b32_e32 v201, v199
	s_nop 0
	v_pk_mul_f32 v[156:157], v[156:157], v[200:201]
	s_branch .LBB0_469
